# conv-tail schedule + nt cache policy on the converter's once-read f32 weight loads
# speedup vs baseline: 1.0140x; 1.0049x over previous
.LBB0_112:
	s_mul_i32 s5, s5, s10
	v_lshlrev_b32_e32 v0, 4, v34
	s_sub_i32 s5, s2, s5
	v_add_u32_e32 v4, 0x200, v34
	v_and_b32_e32 v184, 0xf0, v0
	s_lshl_b32 s6, s5, 6
	v_ashrrev_i32_e32 v36, 4, v34
	v_ashrrev_i32_e32 v37, 4, v4
	v_lshl_add_u64 v[32:33], s[0:1], 0, v[184:185]
	s_ashr_i32 s5, s4, 31
	v_add_u32_e32 v2, s6, v36
	v_add_u32_e32 v4, s6, v37
	s_waitcnt lgkmcnt(0)
	v_lshl_add_u64 v[0:1], s[4:5], 2, v[32:33]
	v_mad_i64_i32 v[2:3], s[4:5], v2, s14, 0
	v_mad_i64_i32 v[4:5], s[4:5], v4, s14, 0
	v_lshl_add_u64 v[2:3], v[2:3], 2, v[0:1]
	v_lshl_add_u64 v[4:5], v[4:5], 2, v[0:1]
	global_load_dwordx4 v[0:3], v[2:3], off nt
	s_nop 0
	global_load_dwordx4 v[4:7], v[4:5], off nt
	s_cmp_ge_i32 s76, s11
	s_cbranch_scc1 .LBB0_146
	v_readlane_b32 s6, v254, 21
	s_mul_hi_u32 s4, s6, s15
	s_mul_i32 s5, s4, s10
	s_sub_i32 s5, s6, s5
	s_add_i32 s6, s4, 1
	s_sub_i32 s7, s5, s10
	s_cmp_ge_u32 s5, s10
	s_cselect_b32 s4, s6, s4
	s_cselect_b32 s5, s7, s5
	s_add_i32 s6, s4, 1
	s_cmp_ge_u32 s5, s10
	s_cselect_b32 s4, s6, s4
	v_readlane_b32 s5, v254, 20
	s_xor_b32 s4, s4, s5
	s_sub_i32 s5, s4, s5
	s_lshl_b32 s4, s5, 6
	s_cmp_lt_i32 s12, 1
	s_cbranch_scc1 .LBB0_128
	s_cmp_lg_u32 s12, 1
	s_mov_b64 s[6:7], -1
	s_cbranch_scc0 .LBB0_125
	s_cmpk_lt_i32 s4, 0xd00
	s_mov_b32 s38, s4
	s_cbranch_scc1 .LBB0_124
	s_add_i32 s39, s4, 0xfffff300
	s_and_b32 s40, s4, 0xc0
	s_cmpk_lt_u32 s39, 0x400
	s_cbranch_scc1 .LBB0_122
	s_lshr_b32 s6, s39, 1
	s_and_b32 s41, s4, 64
	s_and_b32 s42, s6, 0x7fffff80
	s_cmpk_lt_u32 s40, 0x80
	s_cselect_b64 s[6:7], -1, 0
	s_cmpk_lt_u32 s39, 0xc00
	s_mov_b64 s[8:9], -1
	s_cbranch_scc1 .LBB0_119
	s_and_b64 s[8:9], s[6:7], exec
	s_movk_i32 s8, 0x1100
	s_cselect_b32 s8, s8, 0x1500
	s_add_i32 s9, s42, s41
	s_add_i32 s8, s9, s8
	s_add_i32 s38, s8, 0xfffffa00
	s_mov_b64 s[8:9], 0

.LBB0_128:
	s_mul_i32 s5, s5, s10
	s_sub_i32 s5, s76, s5
	s_lshl_b32 s6, s5, 6
	s_ashr_i32 s5, s4, 31
	v_add_u32_e32 v10, s6, v36
	v_add_u32_e32 v12, s6, v37
	v_lshl_add_u64 v[8:9], s[4:5], 2, v[32:33]
	v_mad_i64_i32 v[10:11], s[4:5], v10, s14, 0
	v_mad_i64_i32 v[12:13], s[4:5], v12, s14, 0
	v_lshl_add_u64 v[10:11], v[10:11], 2, v[8:9]
	v_lshl_add_u64 v[12:13], v[12:13], 2, v[8:9]
	global_load_dwordx4 v[8:11], v[10:11], off nt
	s_nop 0
	global_load_dwordx4 v[12:15], v[12:13], off nt
	s_cmp_ge_i32 s96, s11
	s_cbranch_scc0 .LBB0_147

.LBB0_145:
	s_mul_i32 s5, s5, s10
	s_sub_i32 s5, s71, s5
	s_lshl_b32 s6, s5, 6
	s_ashr_i32 s5, s4, 31
	v_add_u32_e32 v26, s6, v36
	v_add_u32_e32 v28, s6, v37
	v_lshl_add_u64 v[24:25], s[4:5], 2, v[32:33]
	v_mad_i64_i32 v[26:27], s[4:5], v26, s14, 0
	v_mad_i64_i32 v[28:29], s[4:5], v28, s14, 0
	v_lshl_add_u64 v[26:27], v[26:27], 2, v[24:25]
	v_lshl_add_u64 v[28:29], v[28:29], 2, v[24:25]
	global_load_dwordx4 v[24:27], v[26:27], off nt
	s_nop 0
	global_load_dwordx4 v[28:31], v[28:29], off nt
	s_andn2_b64 vcc, exec, s[34:35]
	s_cbranch_vccnz .LBB0_82
	s_branch .LBB0_164

.LBB0_162:
	s_mul_i32 s5, s5, s10
	s_sub_i32 s5, s96, s5
	s_lshl_b32 s6, s5, 6
	s_ashr_i32 s5, s4, 31
	v_add_u32_e32 v18, s6, v36
	v_add_u32_e32 v20, s6, v37
	v_lshl_add_u64 v[16:17], s[4:5], 2, v[32:33]
	v_mad_i64_i32 v[18:19], s[4:5], v18, s14, 0
	v_mad_i64_i32 v[20:21], s[4:5], v20, s14, 0
	v_lshl_add_u64 v[18:19], v[18:19], 2, v[16:17]
	v_lshl_add_u64 v[20:21], v[20:21], 2, v[16:17]
	global_load_dwordx4 v[16:19], v[18:19], off nt
	s_nop 0
	global_load_dwordx4 v[20:23], v[20:21], off nt
	s_cmp_ge_i32 s71, s11
	s_cbranch_scc0 .LBB0_130

.LBB0_200:
	s_mul_i32 s46, s46, s10
	s_sub_i32 s1, s1, s46
	s_lshl_b32 s4, s1, 6
	s_ashr_i32 s1, s0, 31
	s_waitcnt vmcnt(0)
	v_add_u32_e32 v2, s4, v40
	v_add_u32_e32 v4, s4, v41
	s_waitcnt lgkmcnt(0)
	v_lshl_add_u64 v[0:1], s[0:1], 2, v[36:37]
	v_mad_i64_i32 v[2:3], s[0:1], v2, s14, 0
	v_mad_i64_i32 v[4:5], s[0:1], v4, s14, 0
	v_lshl_add_u64 v[2:3], v[2:3], 2, v[0:1]
	v_lshl_add_u64 v[4:5], v[4:5], 2, v[0:1]
	global_load_dwordx4 v[0:3], v[2:3], off nt
	s_nop 0
	global_load_dwordx4 v[4:7], v[4:5], off nt
	s_add_i32 s1, s68, s15
	s_cmp_ge_i32 s1, s11
	s_cbranch_scc1 .LBB0_218
	s_abs_i32 s4, s1
	s_mul_hi_u32 s5, s4, s8
	s_mul_i32 s6, s5, s10
	s_sub_i32 s4, s4, s6
	s_ashr_i32 s0, s1, 31
	s_add_i32 s6, s5, 1
	s_sub_i32 s7, s4, s10
	s_cmp_ge_u32 s4, s10
	s_cselect_b32 s5, s6, s5
	s_cselect_b32 s4, s7, s4
	s_add_i32 s6, s5, 1
	s_cmp_ge_u32 s4, s10
	s_cselect_b32 s4, s6, s5
	s_xor_b32 s4, s4, s0
	s_sub_i32 s46, s4, s0
	s_lshl_b32 s0, s46, 6
	s_cmp_lt_i32 s12, 1
	s_cbranch_scc1 .LBB0_216
	s_cmp_lg_u32 s12, 1
	s_mov_b64 s[4:5], -1
	s_cbranch_scc0 .LBB0_213
	s_cmpk_lt_i32 s0, 0xd00
	s_mov_b32 s47, s0
	s_cbranch_scc1 .LBB0_212
	s_add_i32 s48, s0, 0xfffff300
	s_and_b32 s49, s0, 0xc0
	s_cmpk_lt_u32 s48, 0x400
	s_cbranch_scc1 .LBB0_210
	s_lshr_b32 s4, s48, 1
	s_and_b32 s50, s0, 64
	s_and_b32 s51, s4, 0x7fffff80
	s_cmpk_lt_u32 s49, 0x80
	s_cselect_b64 s[4:5], -1, 0
	s_cmpk_lt_u32 s48, 0xc00
	s_mov_b64 s[6:7], -1
	s_cbranch_scc1 .LBB0_207
	s_and_b64 s[6:7], s[4:5], exec
	s_movk_i32 s6, 0x1100
	s_cselect_b32 s6, s6, 0x1500
	s_add_i32 s7, s51, s50
	s_add_i32 s6, s7, s6
	s_add_i32 s47, s6, 0xfffffa00
	s_mov_b64 s[6:7], 0

.LBB0_216:
	s_mul_i32 s46, s46, s10
	s_sub_i32 s1, s1, s46
	s_lshl_b32 s4, s1, 6
	s_ashr_i32 s1, s0, 31
	v_add_u32_e32 v10, s4, v40
	v_add_u32_e32 v12, s4, v41
	v_lshl_add_u64 v[8:9], s[0:1], 2, v[36:37]
	v_mad_i64_i32 v[10:11], s[0:1], v10, s14, 0
	v_mad_i64_i32 v[12:13], s[0:1], v12, s14, 0
	v_lshl_add_u64 v[10:11], v[10:11], 2, v[8:9]
	v_lshl_add_u64 v[12:13], v[12:13], 2, v[8:9]
	global_load_dwordx4 v[8:11], v[10:11], off nt
	s_nop 0
	global_load_dwordx4 v[12:15], v[12:13], off nt
	s_add_i32 s1, s94, s15
	s_cmp_ge_i32 s1, s11
	s_cbranch_scc0 .LBB0_219

.LBB0_234:
	s_mul_i32 s46, s46, s10
	s_sub_i32 s1, s1, s46
	s_lshl_b32 s4, s1, 6
	s_ashr_i32 s1, s0, 31
	v_add_u32_e32 v18, s4, v40
	v_add_u32_e32 v20, s4, v41
	v_lshl_add_u64 v[16:17], s[0:1], 2, v[36:37]
	v_mad_i64_i32 v[18:19], s[0:1], v18, s14, 0
	v_mad_i64_i32 v[20:21], s[0:1], v20, s14, 0
	v_lshl_add_u64 v[18:19], v[18:19], 2, v[16:17]
	v_lshl_add_u64 v[20:21], v[20:21], 2, v[16:17]
	global_load_dwordx4 v[16:19], v[18:19], off nt
	s_nop 0
	global_load_dwordx4 v[20:23], v[20:21], off nt
	s_add_i32 s1, s95, s15
	s_cmp_ge_i32 s1, s11
	s_cbranch_scc1 .LBB0_251

.LBB0_250:
	s_mul_i32 s46, s46, s10
	s_sub_i32 s1, s1, s46
	s_lshl_b32 s4, s1, 6
	s_ashr_i32 s1, s0, 31
	v_add_u32_e32 v26, s4, v40
	v_add_u32_e32 v28, s4, v41
	v_lshl_add_u64 v[24:25], s[0:1], 2, v[36:37]
	v_mad_i64_i32 v[26:27], s[0:1], v26, s14, 0
	v_mad_i64_i32 v[28:29], s[0:1], v28, s14, 0
	v_lshl_add_u64 v[26:27], v[26:27], 2, v[24:25]
	v_lshl_add_u64 v[28:29], v[28:29], 2, v[24:25]
	global_load_dwordx4 v[24:27], v[26:27], off nt
	s_nop 0
	global_load_dwordx4 v[28:31], v[28:29], off nt
